# SwiGLU epilogues: 3-add row statistic sums and saddr-form stores with one 32-bit lane offset (about 47 fewer VALU per epilogue)
# speedup vs baseline: 1.0021x; 1.0021x over previous
.LBB0_173:
	v_mov_b32_e32 v254, 1.0
	v_lshl_add_u32 v202, s20, 8, v1
	s_and_b32 s71, s55, 1
	s_lshl_b32 s71, s71, 12
	s_add_i32 s71, s71, 0x20000
	v_lshl_add_u32 v206, v1, 4, s71
	v_add_u32_e32 v156, 0x80, v202
	ds_read_b128 v[170:173], v206
	ds_read_b128 v[174:177], v206 offset:256
	ds_read_b128 v[178:181], v206 offset:512
	ds_read_b128 v[182:185], v206 offset:768
	ds_read_b128 v[186:189], v206 offset:2048
	ds_read_b128 v[190:193], v206 offset:2304
	ds_read_b128 v[194:197], v206 offset:2560
	ds_read_b128 v[198:201], v206 offset:2816
	v_pk_mul_f32 v[124:125], v[128:129], v[124:125]
	v_pk_mul_f32 v[122:123], v[126:127], v[122:123]
	v_pk_mul_f32 v[116:117], v[120:121], v[116:117]
	v_lshl_or_b32 v204, s68, 7, v164
	v_pk_mul_f32 v[114:115], v[118:119], v[114:115]
	v_mul_u32_u24_e32 v207, s67, v202
	v_lshl_add_u32 v207, v204, 1, v207
	v_pk_mul_f32 v[108:109], v[112:113], v[108:109]
	v_pk_mul_f32 v[106:107], v[110:111], v[106:107]
	v_pk_mul_f32 v[100:101], v[104:105], v[100:101]
	v_pk_mul_f32 v[98:99], v[102:103], v[98:99]
	v_pk_mul_f32 v[92:93], v[96:97], v[92:93]
	v_pk_mul_f32 v[90:91], v[94:95], v[90:91]
	v_pk_mul_f32 v[84:85], v[88:89], v[84:85]
	v_pk_mul_f32 v[82:83], v[86:87], v[82:83]
	v_pk_mul_f32 v[76:77], v[80:81], v[76:77]
	v_pk_mul_f32 v[74:75], v[78:79], v[74:75]
	v_pk_mul_f32 v[68:69], v[72:73], v[68:69]
	v_pk_mul_f32 v[66:67], v[70:71], v[66:67]
	v_pk_mul_f32 v[60:61], v[64:65], v[60:61]
	v_pk_mul_f32 v[58:59], v[62:63], v[58:59]
	v_pk_mul_f32 v[52:53], v[56:57], v[52:53]
	v_pk_mul_f32 v[50:51], v[54:55], v[50:51]
	v_pk_mul_f32 v[44:45], v[48:49], v[44:45]
	v_pk_mul_f32 v[42:43], v[46:47], v[42:43]
	v_pk_mul_f32 v[36:37], v[40:41], v[36:37]
	v_pk_mul_f32 v[34:35], v[38:39], v[34:35]
	v_pk_mul_f32 v[28:29], v[32:33], v[28:29]
	v_pk_mul_f32 v[26:27], v[30:31], v[26:27]
	v_pk_mul_f32 v[20:21], v[24:25], v[20:21]
	v_pk_mul_f32 v[18:19], v[22:23], v[18:19]
	v_pk_mul_f32 v[12:13], v[16:17], v[12:13]
	v_pk_mul_f32 v[10:11], v[14:15], v[10:11]
	v_pk_mul_f32 v[4:5], v[8:9], v[4:5]
	v_pk_mul_f32 v[2:3], v[6:7], v[2:3]
	s_andn2_b64 vcc, exec, s[2:3]
	s_mov_b64 s[2:3], -1
	v_readlane_b32 s70, v253, 14
	v_readlane_b32 s71, v253, 15
	s_waitcnt lgkmcnt(0)
	v_add_f32_e32 v152, v170, v171
	v_add_f32_e32 v153, v172, v173
	v_add_f32_e32 v149, v152, v153
	v_fmamk_f32 v149, v149, 0x3a800000, v168
	v_add_f32_e32 v174, v174, v175
	v_add_f32_e32 v176, v176, v177
	v_rsq_f32_e32 v163, v149
	v_add_f32_e32 v151, v174, v176
	v_add_f32_e32 v178, v178, v179
	v_add_f32_e32 v180, v180, v181
	v_add_f32_e32 v152, v178, v180
	v_add_f32_e32 v182, v182, v183
	v_add_f32_e32 v184, v184, v185
	v_add_f32_e32 v153, v182, v184
	v_add_f32_e32 v186, v186, v187
	v_add_f32_e32 v188, v188, v189
	v_add_f32_e32 v155, v186, v188
	v_add_f32_e32 v190, v190, v191
	v_add_f32_e32 v192, v192, v193
	v_add_f32_e32 v157, v190, v192
	v_add_f32_e32 v194, v194, v195
	v_add_f32_e32 v196, v196, v197
	v_add_f32_e32 v159, v194, v196
	v_add_f32_e32 v198, v198, v199
	v_add_f32_e32 v200, v200, v201
	v_add_f32_e32 v161, v198, v200
	v_fmamk_f32 v149, v151, 0x3a800000, v168
	v_fmamk_f32 v151, v152, 0x3a800000, v168
	v_fmamk_f32 v152, v153, 0x3a800000, v168
	v_fmamk_f32 v153, v155, 0x3a800000, v168
	v_fmamk_f32 v155, v157, 0x3a800000, v168
	v_fmamk_f32 v157, v159, 0x3a800000, v168
	v_fmamk_f32 v159, v161, 0x3a800000, v168
	v_rsq_f32_e32 v169, v151
	v_rsq_f32_e32 v151, v157
	v_mul_f32_e32 v157, 0xbfb8aa3b, v163
	v_rsq_f32_e32 v161, v149
	v_rsq_f32_e32 v149, v159
	v_pk_mul_f32 v[174:175], v[126:127], v[156:157] op_sel:[0,1] op_sel_hi:[1,1]
	v_exp_f32_e32 v174, v174
	v_exp_f32_e32 v175, v175
	v_mul_f32_e32 v172, v163, v163
	v_pk_add_f32 v[174:175], v[174:175], v[254:255] op_sel_hi:[1,0]
	v_rcp_f32_e32 v174, v174
	v_rcp_f32_e32 v175, v175
	v_pk_mul_f32 v[128:129], v[128:129], v[156:157] op_sel:[0,1] op_sel_hi:[1,1]
	v_exp_f32_e32 v128, v128
	v_exp_f32_e32 v129, v129
	v_rsq_f32_e32 v173, v152
	v_rsq_f32_e32 v176, v153
	v_pk_add_f32 v[128:129], v[128:129], v[254:255] op_sel_hi:[1,0]
	v_rcp_f32_e32 v128, v128
	v_rcp_f32_e32 v129, v129
	v_pk_mul_f32 v[126:127], v[172:173], v[174:175] op_sel_hi:[0,1]
	v_pk_mul_f32 v[122:123], v[122:123], v[126:127]
	v_pk_mul_f32 v[126:127], v[172:173], v[128:129] op_sel_hi:[0,1]
	v_pk_mul_f32 v[128:129], v[118:119], v[156:157] op_sel:[0,1] op_sel_hi:[1,1]
	v_exp_f32_e32 v128, v128
	v_exp_f32_e32 v129, v129
	v_pk_mul_f32 v[124:125], v[124:125], v[126:127]
	v_pk_add_f32 v[126:127], v[128:129], v[254:255] op_sel_hi:[1,0]
	v_mul_f32_e32 v128, v120, v157
	v_mul_f32_e32 v129, v121, v157
	v_exp_f32_e32 v128, v128
	v_exp_f32_e32 v129, v129
	v_rcp_f32_e32 v126, v126
	v_rcp_f32_e32 v127, v127
	v_add_f32_e32 v120, 1.0, v128
	v_add_f32_e32 v121, 1.0, v129
	v_rcp_f32_e32 v120, v120
	v_rcp_f32_e32 v121, v121
	v_pk_mul_f32 v[118:119], v[172:173], v[126:127] op_sel_hi:[0,1]
	v_pk_mul_f32 v[118:119], v[114:115], v[118:119]
	v_rsq_f32_e32 v155, v155
	v_pk_mul_f32 v[114:115], v[172:173], v[120:121] op_sel_hi:[0,1]
	v_pk_mul_f32 v[120:121], v[116:117], v[114:115]
	v_cvt_pk_bf16_f32 v116, v122, v123
	v_cvt_pk_bf16_f32 v117, v124, v125
	v_cvt_pk_bf16_f32 v118, v118, v119
	v_cvt_pk_bf16_f32 v119, v120, v121
	global_store_dwordx4 v207, v[116:119], s[4:5]
	s_nop 1
	v_mul_f32_e32 v119, 0xbfb8aa3b, v161
	v_pk_mul_f32 v[120:121], v[110:111], v[118:119] op_sel:[0,1] op_sel_hi:[1,1]
	v_exp_f32_e32 v120, v120
	v_exp_f32_e32 v121, v121
	v_pk_mul_f32 v[122:123], v[112:113], v[118:119] op_sel:[0,1] op_sel_hi:[1,1]
	v_exp_f32_e32 v122, v122
	v_exp_f32_e32 v123, v123
	v_pk_add_f32 v[120:121], v[120:121], v[254:255] op_sel_hi:[1,0]
	v_rcp_f32_e32 v120, v120
	v_rcp_f32_e32 v121, v121
	v_pk_add_f32 v[122:123], v[122:123], v[254:255] op_sel_hi:[1,0]
	v_rcp_f32_e32 v112, v122
	v_rcp_f32_e32 v113, v123
	v_mul_f32_e32 v118, v161, v161
	v_pk_mul_f32 v[110:111], v[118:119], v[120:121] op_sel_hi:[0,1]
	v_pk_mul_f32 v[106:107], v[106:107], v[110:111]
	v_pk_mul_f32 v[110:111], v[118:119], v[112:113] op_sel_hi:[0,1]
	v_pk_mul_f32 v[112:113], v[102:103], v[118:119] op_sel:[0,1] op_sel_hi:[1,1]
	v_exp_f32_e32 v112, v112
	v_exp_f32_e32 v113, v113
	v_pk_mul_f32 v[108:109], v[108:109], v[110:111]
	v_pk_add_f32 v[110:111], v[112:113], v[254:255] op_sel_hi:[1,0]
	v_pk_mul_f32 v[112:113], v[104:105], v[118:119] op_sel:[0,1] op_sel_hi:[1,1]
	v_exp_f32_e32 v112, v112
	v_exp_f32_e32 v113, v113
	v_rcp_f32_e32 v110, v110
	v_rcp_f32_e32 v111, v111
	v_pk_add_f32 v[112:113], v[112:113], v[254:255] op_sel_hi:[1,0]
	v_rcp_f32_e32 v104, v112
	v_rcp_f32_e32 v105, v113
	v_pk_mul_f32 v[102:103], v[118:119], v[110:111] op_sel_hi:[0,1]
	v_pk_mul_f32 v[102:103], v[98:99], v[102:103]
	v_pk_mul_f32 v[98:99], v[118:119], v[104:105] op_sel_hi:[0,1]
	v_pk_mul_f32 v[104:105], v[100:101], v[98:99]
	v_cvt_pk_bf16_f32 v98, v106, v107
	v_cvt_pk_bf16_f32 v99, v108, v109
	v_cvt_pk_bf16_f32 v100, v102, v103
	v_cvt_pk_bf16_f32 v101, v104, v105
	s_add_u32 s28, s4, 0x16000
	s_addc_u32 s29, s5, 0
	global_store_dwordx4 v207, v[98:101], s[28:29]
	s_nop 1
	v_mul_f32_e32 v101, 0xbfb8aa3b, v169
	v_pk_mul_f32 v[102:103], v[94:95], v[100:101] op_sel:[0,1] op_sel_hi:[1,1]
	v_exp_f32_e32 v102, v102
	v_exp_f32_e32 v103, v103
	v_pk_mul_f32 v[104:105], v[96:97], v[100:101] op_sel:[0,1] op_sel_hi:[1,1]
	v_exp_f32_e32 v104, v104
	v_exp_f32_e32 v105, v105
	v_pk_add_f32 v[102:103], v[102:103], v[254:255] op_sel_hi:[1,0]
	v_rcp_f32_e32 v102, v102
	v_rcp_f32_e32 v103, v103
	v_pk_add_f32 v[104:105], v[104:105], v[254:255] op_sel_hi:[1,0]
	v_rcp_f32_e32 v96, v104
	v_rcp_f32_e32 v97, v105
	v_mul_f32_e32 v100, v169, v169
	v_pk_mul_f32 v[94:95], v[100:101], v[102:103] op_sel_hi:[0,1]
	v_pk_mul_f32 v[90:91], v[90:91], v[94:95]
	v_pk_mul_f32 v[94:95], v[100:101], v[96:97] op_sel_hi:[0,1]
	v_pk_mul_f32 v[96:97], v[86:87], v[100:101] op_sel:[0,1] op_sel_hi:[1,1]
	v_exp_f32_e32 v96, v96
	v_exp_f32_e32 v97, v97
	v_pk_mul_f32 v[92:93], v[92:93], v[94:95]
	v_pk_add_f32 v[94:95], v[96:97], v[254:255] op_sel_hi:[1,0]
	v_pk_mul_f32 v[96:97], v[88:89], v[100:101] op_sel:[0,1] op_sel_hi:[1,1]
	v_exp_f32_e32 v96, v96
	v_exp_f32_e32 v97, v97
	v_rcp_f32_e32 v94, v94
	v_rcp_f32_e32 v95, v95
	v_pk_add_f32 v[96:97], v[96:97], v[254:255] op_sel_hi:[1,0]
	v_rcp_f32_e32 v88, v96
	v_rcp_f32_e32 v89, v97
	v_pk_mul_f32 v[86:87], v[100:101], v[94:95] op_sel_hi:[0,1]
	v_pk_mul_f32 v[86:87], v[82:83], v[86:87]
	v_pk_mul_f32 v[82:83], v[100:101], v[88:89] op_sel_hi:[0,1]
	v_pk_mul_f32 v[88:89], v[84:85], v[82:83]
	v_cvt_pk_bf16_f32 v82, v90, v91
	v_cvt_pk_bf16_f32 v83, v92, v93
	v_cvt_pk_bf16_f32 v84, v86, v87
	v_cvt_pk_bf16_f32 v85, v88, v89
	s_add_u32 s28, s4, 0x2c000
	s_addc_u32 s29, s5, 0
	global_store_dwordx4 v207, v[82:85], s[28:29]
	s_nop 1
	v_mul_f32_e32 v85, 0xbfb8aa3b, v173
	v_pk_mul_f32 v[86:87], v[78:79], v[84:85] op_sel:[0,1] op_sel_hi:[1,1]
	v_exp_f32_e32 v86, v86
	v_exp_f32_e32 v87, v87
	v_pk_mul_f32 v[88:89], v[80:81], v[84:85] op_sel:[0,1] op_sel_hi:[1,1]
	v_exp_f32_e32 v88, v88
	v_exp_f32_e32 v89, v89
	v_pk_add_f32 v[86:87], v[86:87], v[254:255] op_sel_hi:[1,0]
	v_rcp_f32_e32 v86, v86
	v_rcp_f32_e32 v87, v87
	v_pk_add_f32 v[88:89], v[88:89], v[254:255] op_sel_hi:[1,0]
	v_rcp_f32_e32 v80, v88
	v_rcp_f32_e32 v81, v89
	v_mul_f32_e32 v84, v173, v173
	v_pk_mul_f32 v[78:79], v[84:85], v[86:87] op_sel_hi:[0,1]
	v_pk_mul_f32 v[74:75], v[74:75], v[78:79]
	v_pk_mul_f32 v[78:79], v[84:85], v[80:81] op_sel_hi:[0,1]
	v_pk_mul_f32 v[80:81], v[70:71], v[84:85] op_sel:[0,1] op_sel_hi:[1,1]
	v_exp_f32_e32 v80, v80
	v_exp_f32_e32 v81, v81
	v_pk_mul_f32 v[76:77], v[76:77], v[78:79]
	v_pk_add_f32 v[78:79], v[80:81], v[254:255] op_sel_hi:[1,0]
	v_pk_mul_f32 v[80:81], v[72:73], v[84:85] op_sel:[0,1] op_sel_hi:[1,1]
	v_exp_f32_e32 v80, v80
	v_exp_f32_e32 v81, v81
	v_rcp_f32_e32 v78, v78
	v_rcp_f32_e32 v79, v79
	v_pk_add_f32 v[80:81], v[80:81], v[254:255] op_sel_hi:[1,0]
	v_rcp_f32_e32 v72, v80
	v_rcp_f32_e32 v73, v81
	v_pk_mul_f32 v[70:71], v[84:85], v[78:79] op_sel_hi:[0,1]
	v_pk_mul_f32 v[70:71], v[66:67], v[70:71]
	v_pk_mul_f32 v[66:67], v[84:85], v[72:73] op_sel_hi:[0,1]
	v_pk_mul_f32 v[72:73], v[68:69], v[66:67]
	v_cvt_pk_bf16_f32 v66, v74, v75
	v_cvt_pk_bf16_f32 v67, v76, v77
	v_cvt_pk_bf16_f32 v68, v70, v71
	v_cvt_pk_bf16_f32 v69, v72, v73
	s_add_u32 s28, s4, 0x42000
	s_addc_u32 s29, s5, 0
	global_store_dwordx4 v207, v[66:69], s[28:29]
	s_nop 1
	v_mul_f32_e32 v69, 0xbfb8aa3b, v176
	v_pk_mul_f32 v[70:71], v[62:63], v[68:69] op_sel:[0,1] op_sel_hi:[1,1]
	v_exp_f32_e32 v70, v70
	v_exp_f32_e32 v71, v71
	v_pk_mul_f32 v[72:73], v[64:65], v[68:69] op_sel:[0,1] op_sel_hi:[1,1]
	v_exp_f32_e32 v72, v72
	v_exp_f32_e32 v73, v73
	v_pk_add_f32 v[70:71], v[70:71], v[254:255] op_sel_hi:[1,0]
	v_rcp_f32_e32 v70, v70
	v_rcp_f32_e32 v71, v71
	v_pk_add_f32 v[72:73], v[72:73], v[254:255] op_sel_hi:[1,0]
	v_rcp_f32_e32 v64, v72
	v_rcp_f32_e32 v65, v73
	v_mul_f32_e32 v68, v176, v176
	v_pk_mul_f32 v[62:63], v[68:69], v[70:71] op_sel_hi:[0,1]
	v_pk_mul_f32 v[58:59], v[58:59], v[62:63]
	v_pk_mul_f32 v[62:63], v[68:69], v[64:65] op_sel_hi:[0,1]
	v_pk_mul_f32 v[64:65], v[54:55], v[68:69] op_sel:[0,1] op_sel_hi:[1,1]
	v_exp_f32_e32 v64, v64
	v_exp_f32_e32 v65, v65
	v_pk_mul_f32 v[60:61], v[60:61], v[62:63]
	v_pk_add_f32 v[62:63], v[64:65], v[254:255] op_sel_hi:[1,0]
	v_pk_mul_f32 v[64:65], v[56:57], v[68:69] op_sel:[0,1] op_sel_hi:[1,1]
	v_exp_f32_e32 v64, v64
	v_exp_f32_e32 v65, v65
	v_rcp_f32_e32 v62, v62
	v_rcp_f32_e32 v63, v63
	v_pk_add_f32 v[64:65], v[64:65], v[254:255] op_sel_hi:[1,0]
	v_rcp_f32_e32 v56, v64
	v_rcp_f32_e32 v57, v65
	v_pk_mul_f32 v[54:55], v[68:69], v[62:63] op_sel_hi:[0,1]
	v_pk_mul_f32 v[54:55], v[50:51], v[54:55]
	v_pk_mul_f32 v[50:51], v[68:69], v[56:57] op_sel_hi:[0,1]
	v_pk_mul_f32 v[56:57], v[52:53], v[50:51]
	v_cvt_pk_bf16_f32 v50, v58, v59
	v_cvt_pk_bf16_f32 v51, v60, v61
	v_cvt_pk_bf16_f32 v52, v54, v55
	v_cvt_pk_bf16_f32 v53, v56, v57
	s_add_u32 s28, s4, 0xb0000
	s_addc_u32 s29, s5, 0
	global_store_dwordx4 v207, v[50:53], s[28:29]
	s_nop 1
	v_mul_f32_e32 v53, 0xbfb8aa3b, v155
	v_pk_mul_f32 v[54:55], v[46:47], v[52:53] op_sel:[0,1] op_sel_hi:[1,1]
	v_exp_f32_e32 v54, v54
	v_exp_f32_e32 v55, v55
	v_pk_mul_f32 v[56:57], v[48:49], v[52:53] op_sel:[0,1] op_sel_hi:[1,1]
	v_exp_f32_e32 v56, v56
	v_exp_f32_e32 v57, v57
	v_pk_add_f32 v[54:55], v[54:55], v[254:255] op_sel_hi:[1,0]
	v_rcp_f32_e32 v54, v54
	v_rcp_f32_e32 v55, v55
	v_pk_add_f32 v[56:57], v[56:57], v[254:255] op_sel_hi:[1,0]
	v_rcp_f32_e32 v48, v56
	v_rcp_f32_e32 v49, v57
	v_mul_f32_e32 v52, v155, v155
	v_pk_mul_f32 v[46:47], v[52:53], v[54:55] op_sel_hi:[0,1]
	v_pk_mul_f32 v[42:43], v[42:43], v[46:47]
	v_pk_mul_f32 v[46:47], v[52:53], v[48:49] op_sel_hi:[0,1]
	v_pk_mul_f32 v[48:49], v[38:39], v[52:53] op_sel:[0,1] op_sel_hi:[1,1]
	v_exp_f32_e32 v48, v48
	v_exp_f32_e32 v49, v49
	v_pk_mul_f32 v[44:45], v[44:45], v[46:47]
	v_pk_add_f32 v[46:47], v[48:49], v[254:255] op_sel_hi:[1,0]
	v_pk_mul_f32 v[48:49], v[40:41], v[52:53] op_sel:[0,1] op_sel_hi:[1,1]
	v_exp_f32_e32 v48, v48
	v_exp_f32_e32 v49, v49
	v_rcp_f32_e32 v46, v46
	v_rcp_f32_e32 v47, v47
	v_pk_add_f32 v[48:49], v[48:49], v[254:255] op_sel_hi:[1,0]
	v_rcp_f32_e32 v40, v48
	v_rcp_f32_e32 v41, v49
	v_pk_mul_f32 v[38:39], v[52:53], v[46:47] op_sel_hi:[0,1]
	v_pk_mul_f32 v[38:39], v[34:35], v[38:39]
	v_pk_mul_f32 v[34:35], v[52:53], v[40:41] op_sel_hi:[0,1]
	v_pk_mul_f32 v[40:41], v[36:37], v[34:35]
	v_cvt_pk_bf16_f32 v34, v42, v43
	v_cvt_pk_bf16_f32 v35, v44, v45
	v_cvt_pk_bf16_f32 v36, v38, v39
	v_cvt_pk_bf16_f32 v37, v40, v41
	s_add_u32 s28, s4, 0xc6000
	s_addc_u32 s29, s5, 0
	global_store_dwordx4 v207, v[34:37], s[28:29]
	s_nop 1
	v_mul_f32_e32 v37, 0xbfb8aa3b, v151
	v_pk_mul_f32 v[38:39], v[30:31], v[36:37] op_sel:[0,1] op_sel_hi:[1,1]
	v_exp_f32_e32 v38, v38
	v_exp_f32_e32 v39, v39
	v_pk_mul_f32 v[40:41], v[32:33], v[36:37] op_sel:[0,1] op_sel_hi:[1,1]
	v_exp_f32_e32 v40, v40
	v_exp_f32_e32 v41, v41
	v_pk_add_f32 v[38:39], v[38:39], v[254:255] op_sel_hi:[1,0]
	v_rcp_f32_e32 v38, v38
	v_rcp_f32_e32 v39, v39
	v_pk_add_f32 v[40:41], v[40:41], v[254:255] op_sel_hi:[1,0]
	v_rcp_f32_e32 v32, v40
	v_rcp_f32_e32 v33, v41
	v_mul_f32_e32 v36, v151, v151
	v_pk_mul_f32 v[30:31], v[36:37], v[38:39] op_sel_hi:[0,1]
	v_pk_mul_f32 v[26:27], v[26:27], v[30:31]
	v_pk_mul_f32 v[30:31], v[36:37], v[32:33] op_sel_hi:[0,1]
	v_pk_mul_f32 v[32:33], v[22:23], v[36:37] op_sel:[0,1] op_sel_hi:[1,1]
	v_exp_f32_e32 v32, v32
	v_exp_f32_e32 v33, v33
	v_pk_mul_f32 v[28:29], v[28:29], v[30:31]
	v_pk_add_f32 v[30:31], v[32:33], v[254:255] op_sel_hi:[1,0]
	v_pk_mul_f32 v[32:33], v[24:25], v[36:37] op_sel:[0,1] op_sel_hi:[1,1]
	v_exp_f32_e32 v32, v32
	v_exp_f32_e32 v33, v33
	v_rcp_f32_e32 v30, v30
	v_rcp_f32_e32 v31, v31
	v_pk_add_f32 v[32:33], v[32:33], v[254:255] op_sel_hi:[1,0]
	v_rcp_f32_e32 v24, v32
	v_rcp_f32_e32 v25, v33
	v_pk_mul_f32 v[22:23], v[36:37], v[30:31] op_sel_hi:[0,1]
	v_pk_mul_f32 v[22:23], v[18:19], v[22:23]
	v_pk_mul_f32 v[18:19], v[36:37], v[24:25] op_sel_hi:[0,1]
	v_pk_mul_f32 v[24:25], v[20:21], v[18:19]
	v_cvt_pk_bf16_f32 v18, v26, v27
	v_cvt_pk_bf16_f32 v19, v28, v29
	v_cvt_pk_bf16_f32 v20, v22, v23
	v_cvt_pk_bf16_f32 v21, v24, v25
	s_add_u32 s28, s4, 0xdc000
	s_addc_u32 s29, s5, 0
	global_store_dwordx4 v207, v[18:21], s[28:29]
	s_nop 1
	v_mul_f32_e32 v21, 0xbfb8aa3b, v149
	v_pk_mul_f32 v[22:23], v[14:15], v[20:21] op_sel:[0,1] op_sel_hi:[1,1]
	v_exp_f32_e32 v22, v22
	v_exp_f32_e32 v23, v23
	v_pk_mul_f32 v[24:25], v[16:17], v[20:21] op_sel:[0,1] op_sel_hi:[1,1]
	v_exp_f32_e32 v24, v24
	v_exp_f32_e32 v25, v25
	v_pk_add_f32 v[22:23], v[22:23], v[254:255] op_sel_hi:[1,0]
	v_rcp_f32_e32 v22, v22
	v_rcp_f32_e32 v23, v23
	v_pk_add_f32 v[24:25], v[24:25], v[254:255] op_sel_hi:[1,0]
	v_rcp_f32_e32 v16, v24
	v_rcp_f32_e32 v17, v25
	v_mul_f32_e32 v20, v149, v149
	v_pk_mul_f32 v[14:15], v[20:21], v[22:23] op_sel_hi:[0,1]
	v_pk_mul_f32 v[10:11], v[10:11], v[14:15]
	v_pk_mul_f32 v[14:15], v[20:21], v[16:17] op_sel_hi:[0,1]
	v_pk_mul_f32 v[16:17], v[6:7], v[20:21] op_sel:[0,1] op_sel_hi:[1,1]
	v_exp_f32_e32 v16, v16
	v_exp_f32_e32 v17, v17
	v_pk_mul_f32 v[12:13], v[12:13], v[14:15]
	v_pk_add_f32 v[14:15], v[16:17], v[254:255] op_sel_hi:[1,0]
	v_pk_mul_f32 v[16:17], v[8:9], v[20:21] op_sel:[0,1] op_sel_hi:[1,1]
	v_exp_f32_e32 v16, v16
	v_exp_f32_e32 v17, v17
	v_rcp_f32_e32 v14, v14
	v_rcp_f32_e32 v15, v15
	v_pk_add_f32 v[16:17], v[16:17], v[254:255] op_sel_hi:[1,0]
	v_rcp_f32_e32 v8, v16
	v_rcp_f32_e32 v9, v17
	v_pk_mul_f32 v[6:7], v[20:21], v[14:15] op_sel_hi:[0,1]
	v_pk_mul_f32 v[6:7], v[2:3], v[6:7]
	v_pk_mul_f32 v[2:3], v[20:21], v[8:9] op_sel_hi:[0,1]
	v_pk_mul_f32 v[8:9], v[4:5], v[2:3]
	v_cvt_pk_bf16_f32 v2, v10, v11
	v_cvt_pk_bf16_f32 v3, v12, v13
	v_cvt_pk_bf16_f32 v4, v6, v7
	v_cvt_pk_bf16_f32 v5, v8, v9
	s_add_u32 s28, s4, 0xf2000
	s_addc_u32 s29, s5, 0
	global_store_dwordx4 v207, v[2:5], s[28:29]
	s_cbranch_vccnz .LBB0_166
	s_andn2_b64 vcc, exec, s[0:1]
	s_cbranch_vccnz .LBB0_165
	s_barrier
	s_branch .LBB0_165

.LBB0_1923:
	v_mov_b32_e32 v254, 1.0
	v_lshl_add_u32 v202, s56, 8, v1
	s_and_b32 s72, s71, 1
	s_lshl_b32 s72, s72, 12
	s_add_i32 s72, s72, 0x20000
	v_lshl_add_u32 v206, v1, 4, s72
	v_add_u32_e32 v156, 0x80, v202
	ds_read_b128 v[170:173], v206
	ds_read_b128 v[174:177], v206 offset:256
	ds_read_b128 v[178:181], v206 offset:512
	ds_read_b128 v[182:185], v206 offset:768
	ds_read_b128 v[186:189], v206 offset:2048
	ds_read_b128 v[190:193], v206 offset:2304
	ds_read_b128 v[194:197], v206 offset:2560
	ds_read_b128 v[198:201], v206 offset:2816
	v_pk_mul_f32 v[124:125], v[128:129], v[124:125]
	v_pk_mul_f32 v[122:123], v[126:127], v[122:123]
	v_pk_mul_f32 v[116:117], v[120:121], v[116:117]
	v_lshl_or_b32 v204, s14, 7, v164
	v_pk_mul_f32 v[114:115], v[118:119], v[114:115]
	v_mul_u32_u24_e32 v207, s70, v202
	v_lshl_add_u32 v207, v204, 1, v207
	v_pk_mul_f32 v[108:109], v[112:113], v[108:109]
	v_pk_mul_f32 v[106:107], v[110:111], v[106:107]
	v_pk_mul_f32 v[100:101], v[104:105], v[100:101]
	v_pk_mul_f32 v[98:99], v[102:103], v[98:99]
	v_pk_mul_f32 v[92:93], v[96:97], v[92:93]
	v_pk_mul_f32 v[90:91], v[94:95], v[90:91]
	v_pk_mul_f32 v[84:85], v[88:89], v[84:85]
	v_pk_mul_f32 v[82:83], v[86:87], v[82:83]
	v_pk_mul_f32 v[76:77], v[80:81], v[76:77]
	v_pk_mul_f32 v[74:75], v[78:79], v[74:75]
	v_pk_mul_f32 v[68:69], v[72:73], v[68:69]
	v_pk_mul_f32 v[66:67], v[70:71], v[66:67]
	v_pk_mul_f32 v[60:61], v[64:65], v[60:61]
	v_pk_mul_f32 v[58:59], v[62:63], v[58:59]
	v_pk_mul_f32 v[52:53], v[56:57], v[52:53]
	v_pk_mul_f32 v[50:51], v[54:55], v[50:51]
	v_pk_mul_f32 v[44:45], v[48:49], v[44:45]
	v_pk_mul_f32 v[42:43], v[46:47], v[42:43]
	v_pk_mul_f32 v[36:37], v[40:41], v[36:37]
	v_pk_mul_f32 v[34:35], v[38:39], v[34:35]
	v_pk_mul_f32 v[28:29], v[32:33], v[28:29]
	v_pk_mul_f32 v[26:27], v[30:31], v[26:27]
	v_pk_mul_f32 v[20:21], v[24:25], v[20:21]
	v_pk_mul_f32 v[18:19], v[22:23], v[18:19]
	v_pk_mul_f32 v[12:13], v[16:17], v[12:13]
	v_pk_mul_f32 v[10:11], v[14:15], v[10:11]
	v_pk_mul_f32 v[4:5], v[8:9], v[4:5]
	v_pk_mul_f32 v[2:3], v[6:7], v[2:3]
	s_andn2_b64 vcc, exec, s[46:47]
	s_waitcnt lgkmcnt(0)
	v_add_f32_e32 v152, v170, v171
	v_add_f32_e32 v153, v172, v173
	v_add_f32_e32 v149, v152, v153
	v_fmamk_f32 v149, v149, 0x3a800000, v168
	v_add_f32_e32 v174, v174, v175
	v_add_f32_e32 v176, v176, v177
	v_rsq_f32_e32 v163, v149
	v_add_f32_e32 v151, v174, v176
	v_add_f32_e32 v178, v178, v179
	v_add_f32_e32 v180, v180, v181
	v_add_f32_e32 v152, v178, v180
	v_add_f32_e32 v182, v182, v183
	v_add_f32_e32 v184, v184, v185
	v_add_f32_e32 v153, v182, v184
	v_add_f32_e32 v186, v186, v187
	v_add_f32_e32 v188, v188, v189
	v_add_f32_e32 v155, v186, v188
	v_add_f32_e32 v190, v190, v191
	v_add_f32_e32 v192, v192, v193
	v_add_f32_e32 v157, v190, v192
	v_add_f32_e32 v194, v194, v195
	v_add_f32_e32 v196, v196, v197
	v_add_f32_e32 v159, v194, v196
	v_add_f32_e32 v198, v198, v199
	v_add_f32_e32 v200, v200, v201
	v_add_f32_e32 v161, v198, v200
	v_fmamk_f32 v149, v151, 0x3a800000, v168
	v_fmamk_f32 v151, v152, 0x3a800000, v168
	v_fmamk_f32 v152, v153, 0x3a800000, v168
	v_fmamk_f32 v153, v155, 0x3a800000, v168
	v_fmamk_f32 v155, v157, 0x3a800000, v168
	v_fmamk_f32 v157, v159, 0x3a800000, v168
	v_fmamk_f32 v159, v161, 0x3a800000, v168
	v_rsq_f32_e32 v169, v151
	v_rsq_f32_e32 v151, v157
	v_mul_f32_e32 v157, 0xbfb8aa3b, v163
	v_rsq_f32_e32 v161, v149
	v_rsq_f32_e32 v149, v159
	v_pk_mul_f32 v[174:175], v[126:127], v[156:157] op_sel:[0,1] op_sel_hi:[1,1]
	v_exp_f32_e32 v174, v174
	v_exp_f32_e32 v175, v175
	v_mul_f32_e32 v172, v163, v163
	v_pk_add_f32 v[174:175], v[174:175], v[254:255] op_sel_hi:[1,0]
	v_rcp_f32_e32 v174, v174
	v_rcp_f32_e32 v175, v175
	v_pk_mul_f32 v[128:129], v[128:129], v[156:157] op_sel:[0,1] op_sel_hi:[1,1]
	v_exp_f32_e32 v128, v128
	v_exp_f32_e32 v129, v129
	v_rsq_f32_e32 v173, v152
	v_rsq_f32_e32 v176, v153
	v_pk_add_f32 v[128:129], v[128:129], v[254:255] op_sel_hi:[1,0]
	v_rcp_f32_e32 v128, v128
	v_rcp_f32_e32 v129, v129
	v_pk_mul_f32 v[126:127], v[172:173], v[174:175] op_sel_hi:[0,1]
	v_pk_mul_f32 v[122:123], v[122:123], v[126:127]
	v_pk_mul_f32 v[126:127], v[172:173], v[128:129] op_sel_hi:[0,1]
	v_pk_mul_f32 v[128:129], v[118:119], v[156:157] op_sel:[0,1] op_sel_hi:[1,1]
	v_exp_f32_e32 v128, v128
	v_exp_f32_e32 v129, v129
	v_pk_mul_f32 v[124:125], v[124:125], v[126:127]
	v_pk_add_f32 v[126:127], v[128:129], v[254:255] op_sel_hi:[1,0]
	v_mul_f32_e32 v128, v120, v157
	v_mul_f32_e32 v129, v121, v157
	v_exp_f32_e32 v128, v128
	v_exp_f32_e32 v129, v129
	v_rcp_f32_e32 v126, v126
	v_rcp_f32_e32 v127, v127
	v_add_f32_e32 v120, 1.0, v128
	v_add_f32_e32 v121, 1.0, v129
	v_rcp_f32_e32 v120, v120
	v_rcp_f32_e32 v121, v121
	v_pk_mul_f32 v[118:119], v[172:173], v[126:127] op_sel_hi:[0,1]
	v_pk_mul_f32 v[118:119], v[114:115], v[118:119]
	v_rsq_f32_e32 v155, v155
	v_pk_mul_f32 v[114:115], v[172:173], v[120:121] op_sel_hi:[0,1]
	v_pk_mul_f32 v[120:121], v[116:117], v[114:115]
	v_cvt_pk_bf16_f32 v116, v122, v123
	v_cvt_pk_bf16_f32 v117, v124, v125
	v_cvt_pk_bf16_f32 v118, v118, v119
	v_cvt_pk_bf16_f32 v119, v120, v121
	global_store_dwordx4 v207, v[116:119], s[18:19]
	s_nop 1
	v_mul_f32_e32 v119, 0xbfb8aa3b, v161
	v_pk_mul_f32 v[120:121], v[110:111], v[118:119] op_sel:[0,1] op_sel_hi:[1,1]
	v_exp_f32_e32 v120, v120
	v_exp_f32_e32 v121, v121
	v_pk_mul_f32 v[122:123], v[112:113], v[118:119] op_sel:[0,1] op_sel_hi:[1,1]
	v_exp_f32_e32 v122, v122
	v_exp_f32_e32 v123, v123
	v_pk_add_f32 v[120:121], v[120:121], v[254:255] op_sel_hi:[1,0]
	v_rcp_f32_e32 v120, v120
	v_rcp_f32_e32 v121, v121
	v_pk_add_f32 v[122:123], v[122:123], v[254:255] op_sel_hi:[1,0]
	v_rcp_f32_e32 v112, v122
	v_rcp_f32_e32 v113, v123
	v_mul_f32_e32 v118, v161, v161
	v_pk_mul_f32 v[110:111], v[118:119], v[120:121] op_sel_hi:[0,1]
	v_pk_mul_f32 v[106:107], v[106:107], v[110:111]
	v_pk_mul_f32 v[110:111], v[118:119], v[112:113] op_sel_hi:[0,1]
	v_pk_mul_f32 v[112:113], v[102:103], v[118:119] op_sel:[0,1] op_sel_hi:[1,1]
	v_exp_f32_e32 v112, v112
	v_exp_f32_e32 v113, v113
	v_pk_mul_f32 v[108:109], v[108:109], v[110:111]
	v_pk_add_f32 v[110:111], v[112:113], v[254:255] op_sel_hi:[1,0]
	v_pk_mul_f32 v[112:113], v[104:105], v[118:119] op_sel:[0,1] op_sel_hi:[1,1]
	v_exp_f32_e32 v112, v112
	v_exp_f32_e32 v113, v113
	v_rcp_f32_e32 v110, v110
	v_rcp_f32_e32 v111, v111
	v_pk_add_f32 v[112:113], v[112:113], v[254:255] op_sel_hi:[1,0]
	v_rcp_f32_e32 v104, v112
	v_rcp_f32_e32 v105, v113
	v_pk_mul_f32 v[102:103], v[118:119], v[110:111] op_sel_hi:[0,1]
	v_pk_mul_f32 v[102:103], v[98:99], v[102:103]
	v_pk_mul_f32 v[98:99], v[118:119], v[104:105] op_sel_hi:[0,1]
	v_pk_mul_f32 v[104:105], v[100:101], v[98:99]
	v_cvt_pk_bf16_f32 v98, v106, v107
	v_cvt_pk_bf16_f32 v99, v108, v109
	v_cvt_pk_bf16_f32 v100, v102, v103
	v_cvt_pk_bf16_f32 v101, v104, v105
	s_add_u32 s28, s18, 0x16000
	s_addc_u32 s29, s19, 0
	global_store_dwordx4 v207, v[98:101], s[28:29]
	s_nop 1
	v_mul_f32_e32 v101, 0xbfb8aa3b, v169
	v_pk_mul_f32 v[102:103], v[94:95], v[100:101] op_sel:[0,1] op_sel_hi:[1,1]
	v_exp_f32_e32 v102, v102
	v_exp_f32_e32 v103, v103
	v_pk_mul_f32 v[104:105], v[96:97], v[100:101] op_sel:[0,1] op_sel_hi:[1,1]
	v_exp_f32_e32 v104, v104
	v_exp_f32_e32 v105, v105
	v_pk_add_f32 v[102:103], v[102:103], v[254:255] op_sel_hi:[1,0]
	v_rcp_f32_e32 v102, v102
	v_rcp_f32_e32 v103, v103
	v_pk_add_f32 v[104:105], v[104:105], v[254:255] op_sel_hi:[1,0]
	v_rcp_f32_e32 v96, v104
	v_rcp_f32_e32 v97, v105
	v_mul_f32_e32 v100, v169, v169
	v_pk_mul_f32 v[94:95], v[100:101], v[102:103] op_sel_hi:[0,1]
	v_pk_mul_f32 v[90:91], v[90:91], v[94:95]
	v_pk_mul_f32 v[94:95], v[100:101], v[96:97] op_sel_hi:[0,1]
	v_pk_mul_f32 v[96:97], v[86:87], v[100:101] op_sel:[0,1] op_sel_hi:[1,1]
	v_exp_f32_e32 v96, v96
	v_exp_f32_e32 v97, v97
	v_pk_mul_f32 v[92:93], v[92:93], v[94:95]
	v_pk_add_f32 v[94:95], v[96:97], v[254:255] op_sel_hi:[1,0]
	v_pk_mul_f32 v[96:97], v[88:89], v[100:101] op_sel:[0,1] op_sel_hi:[1,1]
	v_exp_f32_e32 v96, v96
	v_exp_f32_e32 v97, v97
	v_rcp_f32_e32 v94, v94
	v_rcp_f32_e32 v95, v95
	v_pk_add_f32 v[96:97], v[96:97], v[254:255] op_sel_hi:[1,0]
	v_rcp_f32_e32 v88, v96
	v_rcp_f32_e32 v89, v97
	v_pk_mul_f32 v[86:87], v[100:101], v[94:95] op_sel_hi:[0,1]
	v_pk_mul_f32 v[86:87], v[82:83], v[86:87]
	v_pk_mul_f32 v[82:83], v[100:101], v[88:89] op_sel_hi:[0,1]
	v_pk_mul_f32 v[88:89], v[84:85], v[82:83]
	v_cvt_pk_bf16_f32 v82, v90, v91
	v_cvt_pk_bf16_f32 v83, v92, v93
	v_cvt_pk_bf16_f32 v84, v86, v87
	v_cvt_pk_bf16_f32 v85, v88, v89
	s_add_u32 s28, s18, 0x2c000
	s_addc_u32 s29, s19, 0
	global_store_dwordx4 v207, v[82:85], s[28:29]
	s_nop 1
	v_mul_f32_e32 v85, 0xbfb8aa3b, v173
	v_pk_mul_f32 v[86:87], v[78:79], v[84:85] op_sel:[0,1] op_sel_hi:[1,1]
	v_exp_f32_e32 v86, v86
	v_exp_f32_e32 v87, v87
	v_pk_mul_f32 v[88:89], v[80:81], v[84:85] op_sel:[0,1] op_sel_hi:[1,1]
	v_exp_f32_e32 v88, v88
	v_exp_f32_e32 v89, v89
	v_pk_add_f32 v[86:87], v[86:87], v[254:255] op_sel_hi:[1,0]
	v_rcp_f32_e32 v86, v86
	v_rcp_f32_e32 v87, v87
	v_pk_add_f32 v[88:89], v[88:89], v[254:255] op_sel_hi:[1,0]
	v_rcp_f32_e32 v80, v88
	v_rcp_f32_e32 v81, v89
	v_mul_f32_e32 v84, v173, v173
	v_pk_mul_f32 v[78:79], v[84:85], v[86:87] op_sel_hi:[0,1]
	v_pk_mul_f32 v[74:75], v[74:75], v[78:79]
	v_pk_mul_f32 v[78:79], v[84:85], v[80:81] op_sel_hi:[0,1]
	v_pk_mul_f32 v[80:81], v[70:71], v[84:85] op_sel:[0,1] op_sel_hi:[1,1]
	v_exp_f32_e32 v80, v80
	v_exp_f32_e32 v81, v81
	v_pk_mul_f32 v[76:77], v[76:77], v[78:79]
	v_pk_add_f32 v[78:79], v[80:81], v[254:255] op_sel_hi:[1,0]
	v_pk_mul_f32 v[80:81], v[72:73], v[84:85] op_sel:[0,1] op_sel_hi:[1,1]
	v_exp_f32_e32 v80, v80
	v_exp_f32_e32 v81, v81
	v_rcp_f32_e32 v78, v78
	v_rcp_f32_e32 v79, v79
	v_pk_add_f32 v[80:81], v[80:81], v[254:255] op_sel_hi:[1,0]
	v_rcp_f32_e32 v72, v80
	v_rcp_f32_e32 v73, v81
	v_pk_mul_f32 v[70:71], v[84:85], v[78:79] op_sel_hi:[0,1]
	v_pk_mul_f32 v[70:71], v[66:67], v[70:71]
	v_pk_mul_f32 v[66:67], v[84:85], v[72:73] op_sel_hi:[0,1]
	v_pk_mul_f32 v[72:73], v[68:69], v[66:67]
	v_cvt_pk_bf16_f32 v66, v74, v75
	v_cvt_pk_bf16_f32 v67, v76, v77
	v_cvt_pk_bf16_f32 v68, v70, v71
	v_cvt_pk_bf16_f32 v69, v72, v73
	s_add_u32 s28, s18, 0x42000
	s_addc_u32 s29, s19, 0
	global_store_dwordx4 v207, v[66:69], s[28:29]
	s_nop 1
	v_mul_f32_e32 v69, 0xbfb8aa3b, v176
	v_pk_mul_f32 v[70:71], v[62:63], v[68:69] op_sel:[0,1] op_sel_hi:[1,1]
	v_exp_f32_e32 v70, v70
	v_exp_f32_e32 v71, v71
	v_pk_mul_f32 v[72:73], v[64:65], v[68:69] op_sel:[0,1] op_sel_hi:[1,1]
	v_exp_f32_e32 v72, v72
	v_exp_f32_e32 v73, v73
	v_pk_add_f32 v[70:71], v[70:71], v[254:255] op_sel_hi:[1,0]
	v_rcp_f32_e32 v70, v70
	v_rcp_f32_e32 v71, v71
	v_pk_add_f32 v[72:73], v[72:73], v[254:255] op_sel_hi:[1,0]
	v_rcp_f32_e32 v64, v72
	v_rcp_f32_e32 v65, v73
	v_mul_f32_e32 v68, v176, v176
	v_pk_mul_f32 v[62:63], v[68:69], v[70:71] op_sel_hi:[0,1]
	v_pk_mul_f32 v[58:59], v[58:59], v[62:63]
	v_pk_mul_f32 v[62:63], v[68:69], v[64:65] op_sel_hi:[0,1]
	v_pk_mul_f32 v[64:65], v[54:55], v[68:69] op_sel:[0,1] op_sel_hi:[1,1]
	v_exp_f32_e32 v64, v64
	v_exp_f32_e32 v65, v65
	v_pk_mul_f32 v[60:61], v[60:61], v[62:63]
	v_pk_add_f32 v[62:63], v[64:65], v[254:255] op_sel_hi:[1,0]
	v_pk_mul_f32 v[64:65], v[56:57], v[68:69] op_sel:[0,1] op_sel_hi:[1,1]
	v_exp_f32_e32 v64, v64
	v_exp_f32_e32 v65, v65
	v_rcp_f32_e32 v62, v62
	v_rcp_f32_e32 v63, v63
	v_pk_add_f32 v[64:65], v[64:65], v[254:255] op_sel_hi:[1,0]
	v_rcp_f32_e32 v56, v64
	v_rcp_f32_e32 v57, v65
	v_pk_mul_f32 v[54:55], v[68:69], v[62:63] op_sel_hi:[0,1]
	v_pk_mul_f32 v[54:55], v[50:51], v[54:55]
	v_pk_mul_f32 v[50:51], v[68:69], v[56:57] op_sel_hi:[0,1]
	v_pk_mul_f32 v[56:57], v[52:53], v[50:51]
	v_cvt_pk_bf16_f32 v50, v58, v59
	v_cvt_pk_bf16_f32 v51, v60, v61
	v_cvt_pk_bf16_f32 v52, v54, v55
	v_cvt_pk_bf16_f32 v53, v56, v57
	s_add_u32 s28, s18, 0xb0000
	s_addc_u32 s29, s19, 0
	global_store_dwordx4 v207, v[50:53], s[28:29]
	s_nop 1
	v_mul_f32_e32 v53, 0xbfb8aa3b, v155
	v_pk_mul_f32 v[54:55], v[46:47], v[52:53] op_sel:[0,1] op_sel_hi:[1,1]
	v_exp_f32_e32 v54, v54
	v_exp_f32_e32 v55, v55
	v_pk_mul_f32 v[56:57], v[48:49], v[52:53] op_sel:[0,1] op_sel_hi:[1,1]
	v_exp_f32_e32 v56, v56
	v_exp_f32_e32 v57, v57
	v_pk_add_f32 v[54:55], v[54:55], v[254:255] op_sel_hi:[1,0]
	v_rcp_f32_e32 v54, v54
	v_rcp_f32_e32 v55, v55
	v_pk_add_f32 v[56:57], v[56:57], v[254:255] op_sel_hi:[1,0]
	v_rcp_f32_e32 v48, v56
	v_rcp_f32_e32 v49, v57
	v_mul_f32_e32 v52, v155, v155
	v_pk_mul_f32 v[46:47], v[52:53], v[54:55] op_sel_hi:[0,1]
	v_pk_mul_f32 v[42:43], v[42:43], v[46:47]
	v_pk_mul_f32 v[46:47], v[52:53], v[48:49] op_sel_hi:[0,1]
	v_pk_mul_f32 v[48:49], v[38:39], v[52:53] op_sel:[0,1] op_sel_hi:[1,1]
	v_exp_f32_e32 v48, v48
	v_exp_f32_e32 v49, v49
	v_pk_mul_f32 v[44:45], v[44:45], v[46:47]
	v_pk_add_f32 v[46:47], v[48:49], v[254:255] op_sel_hi:[1,0]
	v_pk_mul_f32 v[48:49], v[40:41], v[52:53] op_sel:[0,1] op_sel_hi:[1,1]
	v_exp_f32_e32 v48, v48
	v_exp_f32_e32 v49, v49
	v_rcp_f32_e32 v46, v46
	v_rcp_f32_e32 v47, v47
	v_pk_add_f32 v[48:49], v[48:49], v[254:255] op_sel_hi:[1,0]
	v_rcp_f32_e32 v40, v48
	v_rcp_f32_e32 v41, v49
	v_pk_mul_f32 v[38:39], v[52:53], v[46:47] op_sel_hi:[0,1]
	v_pk_mul_f32 v[38:39], v[34:35], v[38:39]
	v_pk_mul_f32 v[34:35], v[52:53], v[40:41] op_sel_hi:[0,1]
	v_pk_mul_f32 v[40:41], v[36:37], v[34:35]
	v_cvt_pk_bf16_f32 v34, v42, v43
	v_cvt_pk_bf16_f32 v35, v44, v45
	v_cvt_pk_bf16_f32 v36, v38, v39
	v_cvt_pk_bf16_f32 v37, v40, v41
	s_add_u32 s28, s18, 0xc6000
	s_addc_u32 s29, s19, 0
	global_store_dwordx4 v207, v[34:37], s[28:29]
	s_nop 1
	v_mul_f32_e32 v37, 0xbfb8aa3b, v151
	v_pk_mul_f32 v[38:39], v[30:31], v[36:37] op_sel:[0,1] op_sel_hi:[1,1]
	v_exp_f32_e32 v38, v38
	v_exp_f32_e32 v39, v39
	v_pk_mul_f32 v[40:41], v[32:33], v[36:37] op_sel:[0,1] op_sel_hi:[1,1]
	v_exp_f32_e32 v40, v40
	v_exp_f32_e32 v41, v41
	v_pk_add_f32 v[38:39], v[38:39], v[254:255] op_sel_hi:[1,0]
	v_rcp_f32_e32 v38, v38
	v_rcp_f32_e32 v39, v39
	v_pk_add_f32 v[40:41], v[40:41], v[254:255] op_sel_hi:[1,0]
	v_rcp_f32_e32 v32, v40
	v_rcp_f32_e32 v33, v41
	v_mul_f32_e32 v36, v151, v151
	v_pk_mul_f32 v[30:31], v[36:37], v[38:39] op_sel_hi:[0,1]
	v_pk_mul_f32 v[26:27], v[26:27], v[30:31]
	v_pk_mul_f32 v[30:31], v[36:37], v[32:33] op_sel_hi:[0,1]
	v_pk_mul_f32 v[32:33], v[22:23], v[36:37] op_sel:[0,1] op_sel_hi:[1,1]
	v_exp_f32_e32 v32, v32
	v_exp_f32_e32 v33, v33
	v_pk_mul_f32 v[28:29], v[28:29], v[30:31]
	v_pk_add_f32 v[30:31], v[32:33], v[254:255] op_sel_hi:[1,0]
	v_pk_mul_f32 v[32:33], v[24:25], v[36:37] op_sel:[0,1] op_sel_hi:[1,1]
	v_exp_f32_e32 v32, v32
	v_exp_f32_e32 v33, v33
	v_rcp_f32_e32 v30, v30
	v_rcp_f32_e32 v31, v31
	v_pk_add_f32 v[32:33], v[32:33], v[254:255] op_sel_hi:[1,0]
	v_rcp_f32_e32 v24, v32
	v_rcp_f32_e32 v25, v33
	v_pk_mul_f32 v[22:23], v[36:37], v[30:31] op_sel_hi:[0,1]
	v_pk_mul_f32 v[22:23], v[18:19], v[22:23]
	v_pk_mul_f32 v[18:19], v[36:37], v[24:25] op_sel_hi:[0,1]
	v_pk_mul_f32 v[24:25], v[20:21], v[18:19]
	v_cvt_pk_bf16_f32 v18, v26, v27
	v_cvt_pk_bf16_f32 v19, v28, v29
	v_cvt_pk_bf16_f32 v20, v22, v23
	v_cvt_pk_bf16_f32 v21, v24, v25
	s_add_u32 s28, s18, 0xdc000
	s_addc_u32 s29, s19, 0
	global_store_dwordx4 v207, v[18:21], s[28:29]
	s_nop 1
	v_mul_f32_e32 v21, 0xbfb8aa3b, v149
	v_pk_mul_f32 v[22:23], v[14:15], v[20:21] op_sel:[0,1] op_sel_hi:[1,1]
	v_exp_f32_e32 v22, v22
	v_exp_f32_e32 v23, v23
	v_pk_mul_f32 v[24:25], v[16:17], v[20:21] op_sel:[0,1] op_sel_hi:[1,1]
	v_exp_f32_e32 v24, v24
	v_exp_f32_e32 v25, v25
	v_pk_add_f32 v[22:23], v[22:23], v[254:255] op_sel_hi:[1,0]
	v_rcp_f32_e32 v22, v22
	v_rcp_f32_e32 v23, v23
	v_pk_add_f32 v[24:25], v[24:25], v[254:255] op_sel_hi:[1,0]
	v_rcp_f32_e32 v16, v24
	v_rcp_f32_e32 v17, v25
	v_mul_f32_e32 v20, v149, v149
	v_pk_mul_f32 v[14:15], v[20:21], v[22:23] op_sel_hi:[0,1]
	v_pk_mul_f32 v[10:11], v[10:11], v[14:15]
	v_pk_mul_f32 v[14:15], v[20:21], v[16:17] op_sel_hi:[0,1]
	v_pk_mul_f32 v[16:17], v[6:7], v[20:21] op_sel:[0,1] op_sel_hi:[1,1]
	v_exp_f32_e32 v16, v16
	v_exp_f32_e32 v17, v17
	v_pk_mul_f32 v[12:13], v[12:13], v[14:15]
	v_pk_add_f32 v[14:15], v[16:17], v[254:255] op_sel_hi:[1,0]
	v_pk_mul_f32 v[16:17], v[8:9], v[20:21] op_sel:[0,1] op_sel_hi:[1,1]
	v_exp_f32_e32 v16, v16
	v_exp_f32_e32 v17, v17
	v_rcp_f32_e32 v14, v14
	v_rcp_f32_e32 v15, v15
	v_pk_add_f32 v[16:17], v[16:17], v[254:255] op_sel_hi:[1,0]
	v_rcp_f32_e32 v8, v16
	v_rcp_f32_e32 v9, v17
	v_pk_mul_f32 v[6:7], v[20:21], v[14:15] op_sel_hi:[0,1]
	v_pk_mul_f32 v[6:7], v[2:3], v[6:7]
	v_pk_mul_f32 v[2:3], v[20:21], v[8:9] op_sel_hi:[0,1]
	v_pk_mul_f32 v[8:9], v[4:5], v[2:3]
	v_cvt_pk_bf16_f32 v2, v10, v11
	v_cvt_pk_bf16_f32 v3, v12, v13
	v_cvt_pk_bf16_f32 v4, v6, v7
	v_cvt_pk_bf16_f32 v5, v8, v9
	s_add_u32 s28, s18, 0xf2000
	s_addc_u32 s29, s19, 0
	global_store_dwordx4 v207, v[2:5], s[28:29]
	s_cbranch_vccnz .LBB0_1929
	s_ashr_i32 s14, s14, 2
	s_cmp_lt_i32 s14, 4
	s_cbranch_scc1 .LBB0_1929
	s_waitcnt vmcnt(0)
	s_and_saveexec_b64 s[28:29], s[2:3]
	s_cbranch_execz .LBB0_1928
	s_mov_b64 s[30:31], exec
	v_mbcnt_lo_u32_b32 v2, s30, 0
	v_mbcnt_hi_u32_b32 v2, s31, v2
	v_cmp_eq_u32_e32 vcc, 0, v2
	s_and_b64 s[58:59], exec, vcc
	s_mov_b64 exec, s[58:59]
	s_cbranch_execz .LBB0_1928
	s_lshl_b32 s14, s14, 6
	s_addk_i32 s14, 0xff00
	s_lshl_b64 s[58:59], s[14:15], 2
	s_add_u32 s58, s38, s58
	s_addc_u32 s59, s39, s59
	s_bcnt1_i32_b64 s14, s[30:31]
	v_mov_b32_e32 v2, s14
	global_atomic_add v133, v2, s[58:59]
